# SwiGLU GEMM epilogue rewritten by hand: ss loads hoisted in 2 batches, rstd batched, no per-row vmcnt(0) drain
# baseline (speedup 1.0000x reference)
.LBB0_343:
	v_and_b32_e32 v145, 64, v220
	v_xor_b32_e32 v144, 16, v220
	v_add_u32_e32 v145, 64, v145
	v_cmp_lt_i32_e32 vcc, v144, v145
	v_lshl_add_u32 v148, s2, 8, v151
	v_lshlrev_b32_e32 v192, 7, v148
	v_cndmask_b32_e32 v144, v220, v144, vcc
	v_lshlrev_b32_e32 v155, 2, v144
	v_xor_b32_e32 v144, 32, v220
	v_cmp_lt_i32_e32 vcc, v144, v145
	v_mov_b32_e32 v193, 0
	v_lshl_or_b32 v146, s0, 7, v153
	v_cndmask_b32_e32 v144, v220, v144, vcc
	v_lshlrev_b32_e32 v156, 2, v144
	v_add_u32_e32 v194, 0x1000, v192
	v_add_u32_e32 v196, 0x4000, v192
	v_add_u32_e32 v198, 0x5000, v192
	v_mov_b32_e32 v195, 0
	v_mov_b32_e32 v197, 0
	v_mov_b32_e32 v199, 0
	v_lshl_add_u64 v[192:193], v[138:139], 0, v[192:193]
	v_lshl_add_u64 v[194:195], v[138:139], 0, v[194:195]
	v_lshl_add_u64 v[196:197], v[138:139], 0, v[196:197]
	v_lshl_add_u64 v[198:199], v[138:139], 0, v[198:199]
	global_load_dwordx4 v[160:163], v[192:193], off
	global_load_dwordx4 v[164:167], v[192:193], off offset:16
	global_load_dwordx4 v[168:171], v[192:193], off offset:2048
	global_load_dwordx4 v[172:175], v[192:193], off offset:2064
	global_load_dwordx4 v[176:179], v[194:195], off
	global_load_dwordx4 v[180:183], v[194:195], off offset:16
	global_load_dwordx4 v[184:187], v[194:195], off offset:2048
	global_load_dwordx4 v[188:191], v[194:195], off offset:2064
	v_ashrrev_i32_e32 v147, 31, v146
	s_movk_i32 s2, 0x2b00
	v_lshlrev_b64 v[146:147], 1, v[146:147]
	v_mov_b64_e32 v[144:145], s[74:75]
	v_lshl_add_u64 v[146:147], v[144:145], 0, v[146:147]
	s_waitcnt vmcnt(0)
	v_add_f32_e32 v160, v160, v161
	v_add_f32_e32 v162, v162, v163
	v_add_f32_e32 v164, v164, v165
	v_add_f32_e32 v166, v166, v167
	v_add_f32_e32 v168, v168, v169
	v_add_f32_e32 v170, v170, v171
	v_add_f32_e32 v172, v172, v173
	v_add_f32_e32 v174, v174, v175
	v_add_f32_e32 v176, v176, v177
	v_add_f32_e32 v178, v178, v179
	v_add_f32_e32 v180, v180, v181
	v_add_f32_e32 v182, v182, v183
	v_add_f32_e32 v184, v184, v185
	v_add_f32_e32 v186, v186, v187
	v_add_f32_e32 v188, v188, v189
	v_add_f32_e32 v190, v190, v191
	v_add_f32_e32 v160, v160, v162
	v_add_f32_e32 v164, v164, v166
	v_add_f32_e32 v168, v168, v170
	v_add_f32_e32 v172, v172, v174
	v_add_f32_e32 v176, v176, v178
	v_add_f32_e32 v180, v180, v182
	v_add_f32_e32 v184, v184, v186
	v_add_f32_e32 v188, v188, v190
	v_add_f32_e32 v200, v160, v164
	v_add_f32_e32 v202, v168, v172
	v_add_f32_e32 v204, v176, v180
	v_add_f32_e32 v206, v184, v188
	global_load_dwordx4 v[160:163], v[196:197], off
	global_load_dwordx4 v[164:167], v[196:197], off offset:16
	global_load_dwordx4 v[168:171], v[196:197], off offset:2048
	global_load_dwordx4 v[172:175], v[196:197], off offset:2064
	global_load_dwordx4 v[176:179], v[198:199], off
	global_load_dwordx4 v[180:183], v[198:199], off offset:16
	global_load_dwordx4 v[184:187], v[198:199], off offset:2048
	global_load_dwordx4 v[188:191], v[198:199], off offset:2064
	ds_bpermute_b32 v201, v155, v200
	ds_bpermute_b32 v203, v155, v202
	ds_bpermute_b32 v205, v155, v204
	ds_bpermute_b32 v207, v155, v206
	s_waitcnt lgkmcnt(0)
	v_add_f32_e32 v200, v200, v201
	v_add_f32_e32 v202, v202, v203
	v_add_f32_e32 v204, v204, v205
	v_add_f32_e32 v206, v206, v207
	ds_bpermute_b32 v201, v156, v200
	ds_bpermute_b32 v203, v156, v202
	ds_bpermute_b32 v205, v156, v204
	ds_bpermute_b32 v207, v156, v206
	s_waitcnt lgkmcnt(0)
	v_add_f32_e32 v200, v200, v201
	v_add_f32_e32 v202, v202, v203
	v_add_f32_e32 v204, v204, v205
	v_add_f32_e32 v206, v206, v207
	v_fmamk_f32 v200, v200, 0x3a000000, v216
	v_cmp_gt_f32_e32 vcc, s65, v200
	v_mul_f32_e32 v201, 0x4b800000, v200
	s_nop 0
	v_cndmask_b32_e32 v200, v200, v201, vcc
	v_rsq_f32_e32 v200, v200
	s_nop 0
	v_mul_f32_e32 v201, 0x45800000, v200
	v_cndmask_b32_e32 v200, v200, v201, vcc
	v_fmamk_f32 v202, v202, 0x3a000000, v216
	v_cmp_gt_f32_e32 vcc, s65, v202
	v_mul_f32_e32 v203, 0x4b800000, v202
	s_nop 0
	v_cndmask_b32_e32 v202, v202, v203, vcc
	v_rsq_f32_e32 v202, v202
	s_nop 0
	v_mul_f32_e32 v203, 0x45800000, v202
	v_cndmask_b32_e32 v202, v202, v203, vcc
	v_fmamk_f32 v204, v204, 0x3a000000, v216
	v_cmp_gt_f32_e32 vcc, s65, v204
	v_mul_f32_e32 v205, 0x4b800000, v204
	s_nop 0
	v_cndmask_b32_e32 v204, v204, v205, vcc
	v_rsq_f32_e32 v204, v204
	s_nop 0
	v_mul_f32_e32 v205, 0x45800000, v204
	v_cndmask_b32_e32 v204, v204, v205, vcc
	v_fmamk_f32 v206, v206, 0x3a000000, v216
	v_cmp_gt_f32_e32 vcc, s65, v206
	v_mul_f32_e32 v207, 0x4b800000, v206
	s_nop 0
	v_cndmask_b32_e32 v206, v206, v207, vcc
	v_rsq_f32_e32 v206, v206
	s_nop 0
	v_mul_f32_e32 v207, 0x45800000, v206
	v_cndmask_b32_e32 v206, v206, v207, vcc
	v_pk_mul_f32 v[126:127], v[126:127], v[200:201] op_sel_hi:[1,0]
	v_pk_mul_f32 v[128:129], v[128:129], v[200:201] op_sel_hi:[1,0]
	v_pk_mul_f32 v[122:123], v[122:123], v[200:201] op_sel_hi:[1,0]
	v_pk_mul_f32 v[124:125], v[124:125], v[200:201] op_sel_hi:[1,0]
	v_pk_mul_f32 v[118:119], v[118:119], v[200:201] op_sel_hi:[1,0]
	v_pk_mul_f32 v[120:121], v[120:121], v[200:201] op_sel_hi:[1,0]
	v_pk_mul_f32 v[114:115], v[114:115], v[200:201] op_sel_hi:[1,0]
	v_pk_mul_f32 v[116:117], v[116:117], v[200:201] op_sel_hi:[1,0]
	v_mul_f32_e32 v208, 0xbfb8aa3b, v126
	v_mul_f32_e32 v209, 0xbfb8aa3b, v127
	v_mul_f32_e32 v210, 0xbfb8aa3b, v128
	v_mul_f32_e32 v211, 0xbfb8aa3b, v129
	v_mul_f32_e32 v232, 0xbfb8aa3b, v122
	v_mul_f32_e32 v233, 0xbfb8aa3b, v123
	v_mul_f32_e32 v234, 0xbfb8aa3b, v124
	v_mul_f32_e32 v235, 0xbfb8aa3b, v125
	v_exp_f32_e32 v208, v208
	v_exp_f32_e32 v209, v209
	v_exp_f32_e32 v210, v210
	v_exp_f32_e32 v211, v211
	v_exp_f32_e32 v232, v232
	v_exp_f32_e32 v233, v233
	v_exp_f32_e32 v234, v234
	v_exp_f32_e32 v235, v235
	v_add_f32_e32 v208, 1.0, v208
	v_add_f32_e32 v209, 1.0, v209
	v_add_f32_e32 v210, 1.0, v210
	v_add_f32_e32 v211, 1.0, v211
	v_add_f32_e32 v232, 1.0, v232
	v_add_f32_e32 v233, 1.0, v233
	v_add_f32_e32 v234, 1.0, v234
	v_add_f32_e32 v235, 1.0, v235
	v_rcp_f32_e32 v208, v208
	v_rcp_f32_e32 v209, v209
	v_rcp_f32_e32 v210, v210
	v_rcp_f32_e32 v211, v211
	v_rcp_f32_e32 v232, v232
	v_rcp_f32_e32 v233, v233
	v_rcp_f32_e32 v234, v234
	v_rcp_f32_e32 v235, v235
	v_pk_mul_f32 v[208:209], v[126:127], v[208:209]
	v_pk_mul_f32 v[210:211], v[128:129], v[210:211]
	v_pk_mul_f32 v[232:233], v[122:123], v[232:233]
	v_pk_mul_f32 v[234:235], v[124:125], v[234:235]
	v_pk_mul_f32 v[208:209], v[118:119], v[208:209]
	v_pk_mul_f32 v[210:211], v[120:121], v[210:211]
	v_pk_mul_f32 v[232:233], v[114:115], v[232:233]
	v_pk_mul_f32 v[234:235], v[116:117], v[234:235]
	v_cvt_pk_bf16_f32 v208, v208, v209
	v_cvt_pk_bf16_f32 v209, v210, v211
	v_cvt_pk_bf16_f32 v210, v232, v233
	v_cvt_pk_bf16_f32 v211, v234, v235
	v_mov_b32_e32 v158, v148
	v_mad_i64_i32 v[158:159], s[0:1], v158, s2, v[146:147]
	global_store_dwordx4 v[158:159], v[208:211], off
	v_pk_mul_f32 v[110:111], v[110:111], v[202:203] op_sel_hi:[1,0]
	v_pk_mul_f32 v[112:113], v[112:113], v[202:203] op_sel_hi:[1,0]
	v_pk_mul_f32 v[106:107], v[106:107], v[202:203] op_sel_hi:[1,0]
	v_pk_mul_f32 v[108:109], v[108:109], v[202:203] op_sel_hi:[1,0]
	v_pk_mul_f32 v[102:103], v[102:103], v[202:203] op_sel_hi:[1,0]
	v_pk_mul_f32 v[104:105], v[104:105], v[202:203] op_sel_hi:[1,0]
	v_pk_mul_f32 v[98:99], v[98:99], v[202:203] op_sel_hi:[1,0]
	v_pk_mul_f32 v[100:101], v[100:101], v[202:203] op_sel_hi:[1,0]
	v_mul_f32_e32 v208, 0xbfb8aa3b, v110
	v_mul_f32_e32 v209, 0xbfb8aa3b, v111
	v_mul_f32_e32 v210, 0xbfb8aa3b, v112
	v_mul_f32_e32 v211, 0xbfb8aa3b, v113
	v_mul_f32_e32 v232, 0xbfb8aa3b, v106
	v_mul_f32_e32 v233, 0xbfb8aa3b, v107
	v_mul_f32_e32 v234, 0xbfb8aa3b, v108
	v_mul_f32_e32 v235, 0xbfb8aa3b, v109
	v_exp_f32_e32 v208, v208
	v_exp_f32_e32 v209, v209
	v_exp_f32_e32 v210, v210
	v_exp_f32_e32 v211, v211
	v_exp_f32_e32 v232, v232
	v_exp_f32_e32 v233, v233
	v_exp_f32_e32 v234, v234
	v_exp_f32_e32 v235, v235
	v_add_f32_e32 v208, 1.0, v208
	v_add_f32_e32 v209, 1.0, v209
	v_add_f32_e32 v210, 1.0, v210
	v_add_f32_e32 v211, 1.0, v211
	v_add_f32_e32 v232, 1.0, v232
	v_add_f32_e32 v233, 1.0, v233
	v_add_f32_e32 v234, 1.0, v234
	v_add_f32_e32 v235, 1.0, v235
	v_rcp_f32_e32 v208, v208
	v_rcp_f32_e32 v209, v209
	v_rcp_f32_e32 v210, v210
	v_rcp_f32_e32 v211, v211
	v_rcp_f32_e32 v232, v232
	v_rcp_f32_e32 v233, v233
	v_rcp_f32_e32 v234, v234
	v_rcp_f32_e32 v235, v235
	v_pk_mul_f32 v[208:209], v[110:111], v[208:209]
	v_pk_mul_f32 v[210:211], v[112:113], v[210:211]
	v_pk_mul_f32 v[232:233], v[106:107], v[232:233]
	v_pk_mul_f32 v[234:235], v[108:109], v[234:235]
	v_pk_mul_f32 v[208:209], v[102:103], v[208:209]
	v_pk_mul_f32 v[210:211], v[104:105], v[210:211]
	v_pk_mul_f32 v[232:233], v[98:99], v[232:233]
	v_pk_mul_f32 v[234:235], v[100:101], v[234:235]
	v_cvt_pk_bf16_f32 v208, v208, v209
	v_cvt_pk_bf16_f32 v209, v210, v211
	v_cvt_pk_bf16_f32 v210, v232, v233
	v_cvt_pk_bf16_f32 v211, v234, v235
	v_add_u32_e32 v158, 0x10, v148
	v_mad_i64_i32 v[158:159], s[0:1], v158, s2, v[146:147]
	global_store_dwordx4 v[158:159], v[208:211], off
	v_pk_mul_f32 v[94:95], v[94:95], v[204:205] op_sel_hi:[1,0]
	v_pk_mul_f32 v[96:97], v[96:97], v[204:205] op_sel_hi:[1,0]
	v_pk_mul_f32 v[90:91], v[90:91], v[204:205] op_sel_hi:[1,0]
	v_pk_mul_f32 v[92:93], v[92:93], v[204:205] op_sel_hi:[1,0]
	v_pk_mul_f32 v[86:87], v[86:87], v[204:205] op_sel_hi:[1,0]
	v_pk_mul_f32 v[88:89], v[88:89], v[204:205] op_sel_hi:[1,0]
	v_pk_mul_f32 v[82:83], v[82:83], v[204:205] op_sel_hi:[1,0]
	v_pk_mul_f32 v[84:85], v[84:85], v[204:205] op_sel_hi:[1,0]
	v_mul_f32_e32 v208, 0xbfb8aa3b, v94
	v_mul_f32_e32 v209, 0xbfb8aa3b, v95
	v_mul_f32_e32 v210, 0xbfb8aa3b, v96
	v_mul_f32_e32 v211, 0xbfb8aa3b, v97
	v_mul_f32_e32 v232, 0xbfb8aa3b, v90
	v_mul_f32_e32 v233, 0xbfb8aa3b, v91
	v_mul_f32_e32 v234, 0xbfb8aa3b, v92
	v_mul_f32_e32 v235, 0xbfb8aa3b, v93
	v_exp_f32_e32 v208, v208
	v_exp_f32_e32 v209, v209
	v_exp_f32_e32 v210, v210
	v_exp_f32_e32 v211, v211
	v_exp_f32_e32 v232, v232
	v_exp_f32_e32 v233, v233
	v_exp_f32_e32 v234, v234
	v_exp_f32_e32 v235, v235
	v_add_f32_e32 v208, 1.0, v208
	v_add_f32_e32 v209, 1.0, v209
	v_add_f32_e32 v210, 1.0, v210
	v_add_f32_e32 v211, 1.0, v211
	v_add_f32_e32 v232, 1.0, v232
	v_add_f32_e32 v233, 1.0, v233
	v_add_f32_e32 v234, 1.0, v234
	v_add_f32_e32 v235, 1.0, v235
	v_rcp_f32_e32 v208, v208
	v_rcp_f32_e32 v209, v209
	v_rcp_f32_e32 v210, v210
	v_rcp_f32_e32 v211, v211
	v_rcp_f32_e32 v232, v232
	v_rcp_f32_e32 v233, v233
	v_rcp_f32_e32 v234, v234
	v_rcp_f32_e32 v235, v235
	v_pk_mul_f32 v[208:209], v[94:95], v[208:209]
	v_pk_mul_f32 v[210:211], v[96:97], v[210:211]
	v_pk_mul_f32 v[232:233], v[90:91], v[232:233]
	v_pk_mul_f32 v[234:235], v[92:93], v[234:235]
	v_pk_mul_f32 v[208:209], v[86:87], v[208:209]
	v_pk_mul_f32 v[210:211], v[88:89], v[210:211]
	v_pk_mul_f32 v[232:233], v[82:83], v[232:233]
	v_pk_mul_f32 v[234:235], v[84:85], v[234:235]
	v_cvt_pk_bf16_f32 v208, v208, v209
	v_cvt_pk_bf16_f32 v209, v210, v211
	v_cvt_pk_bf16_f32 v210, v232, v233
	v_cvt_pk_bf16_f32 v211, v234, v235
	v_add_u32_e32 v158, 0x20, v148
	v_mad_i64_i32 v[158:159], s[0:1], v158, s2, v[146:147]
	global_store_dwordx4 v[158:159], v[208:211], off
	v_pk_mul_f32 v[78:79], v[78:79], v[206:207] op_sel_hi:[1,0]
	v_pk_mul_f32 v[80:81], v[80:81], v[206:207] op_sel_hi:[1,0]
	v_pk_mul_f32 v[74:75], v[74:75], v[206:207] op_sel_hi:[1,0]
	v_pk_mul_f32 v[76:77], v[76:77], v[206:207] op_sel_hi:[1,0]
	v_pk_mul_f32 v[70:71], v[70:71], v[206:207] op_sel_hi:[1,0]
	v_pk_mul_f32 v[72:73], v[72:73], v[206:207] op_sel_hi:[1,0]
	v_pk_mul_f32 v[66:67], v[66:67], v[206:207] op_sel_hi:[1,0]
	v_pk_mul_f32 v[68:69], v[68:69], v[206:207] op_sel_hi:[1,0]
	v_mul_f32_e32 v208, 0xbfb8aa3b, v78
	v_mul_f32_e32 v209, 0xbfb8aa3b, v79
	v_mul_f32_e32 v210, 0xbfb8aa3b, v80
	v_mul_f32_e32 v211, 0xbfb8aa3b, v81
	v_mul_f32_e32 v232, 0xbfb8aa3b, v74
	v_mul_f32_e32 v233, 0xbfb8aa3b, v75
	v_mul_f32_e32 v234, 0xbfb8aa3b, v76
	v_mul_f32_e32 v235, 0xbfb8aa3b, v77
	v_exp_f32_e32 v208, v208
	v_exp_f32_e32 v209, v209
	v_exp_f32_e32 v210, v210
	v_exp_f32_e32 v211, v211
	v_exp_f32_e32 v232, v232
	v_exp_f32_e32 v233, v233
	v_exp_f32_e32 v234, v234
	v_exp_f32_e32 v235, v235
	v_add_f32_e32 v208, 1.0, v208
	v_add_f32_e32 v209, 1.0, v209
	v_add_f32_e32 v210, 1.0, v210
	v_add_f32_e32 v211, 1.0, v211
	v_add_f32_e32 v232, 1.0, v232
	v_add_f32_e32 v233, 1.0, v233
	v_add_f32_e32 v234, 1.0, v234
	v_add_f32_e32 v235, 1.0, v235
	v_rcp_f32_e32 v208, v208
	v_rcp_f32_e32 v209, v209
	v_rcp_f32_e32 v210, v210
	v_rcp_f32_e32 v211, v211
	v_rcp_f32_e32 v232, v232
	v_rcp_f32_e32 v233, v233
	v_rcp_f32_e32 v234, v234
	v_rcp_f32_e32 v235, v235
	v_pk_mul_f32 v[208:209], v[78:79], v[208:209]
	v_pk_mul_f32 v[210:211], v[80:81], v[210:211]
	v_pk_mul_f32 v[232:233], v[74:75], v[232:233]
	v_pk_mul_f32 v[234:235], v[76:77], v[234:235]
	v_pk_mul_f32 v[208:209], v[70:71], v[208:209]
	v_pk_mul_f32 v[210:211], v[72:73], v[210:211]
	v_pk_mul_f32 v[232:233], v[66:67], v[232:233]
	v_pk_mul_f32 v[234:235], v[68:69], v[234:235]
	v_cvt_pk_bf16_f32 v208, v208, v209
	v_cvt_pk_bf16_f32 v209, v210, v211
	v_cvt_pk_bf16_f32 v210, v232, v233
	v_cvt_pk_bf16_f32 v211, v234, v235
	v_add_u32_e32 v158, 0x30, v148
	v_mad_i64_i32 v[158:159], s[0:1], v158, s2, v[146:147]
	global_store_dwordx4 v[158:159], v[208:211], off
	s_waitcnt vmcnt(4)
	v_add_f32_e32 v160, v160, v161
	v_add_f32_e32 v162, v162, v163
	v_add_f32_e32 v164, v164, v165
	v_add_f32_e32 v166, v166, v167
	v_add_f32_e32 v168, v168, v169
	v_add_f32_e32 v170, v170, v171
	v_add_f32_e32 v172, v172, v173
	v_add_f32_e32 v174, v174, v175
	v_add_f32_e32 v176, v176, v177
	v_add_f32_e32 v178, v178, v179
	v_add_f32_e32 v180, v180, v181
	v_add_f32_e32 v182, v182, v183
	v_add_f32_e32 v184, v184, v185
	v_add_f32_e32 v186, v186, v187
	v_add_f32_e32 v188, v188, v189
	v_add_f32_e32 v190, v190, v191
	v_add_f32_e32 v160, v160, v162
	v_add_f32_e32 v164, v164, v166
	v_add_f32_e32 v168, v168, v170
	v_add_f32_e32 v172, v172, v174
	v_add_f32_e32 v176, v176, v178
	v_add_f32_e32 v180, v180, v182
	v_add_f32_e32 v184, v184, v186
	v_add_f32_e32 v188, v188, v190
	v_add_f32_e32 v200, v160, v164
	v_add_f32_e32 v202, v168, v172
	v_add_f32_e32 v204, v176, v180
	v_add_f32_e32 v206, v184, v188
	ds_bpermute_b32 v201, v155, v200
	ds_bpermute_b32 v203, v155, v202
	ds_bpermute_b32 v205, v155, v204
	ds_bpermute_b32 v207, v155, v206
	s_waitcnt lgkmcnt(0)
	v_add_f32_e32 v200, v200, v201
	v_add_f32_e32 v202, v202, v203
	v_add_f32_e32 v204, v204, v205
	v_add_f32_e32 v206, v206, v207
	ds_bpermute_b32 v201, v156, v200
	ds_bpermute_b32 v203, v156, v202
	ds_bpermute_b32 v205, v156, v204
	ds_bpermute_b32 v207, v156, v206
	s_waitcnt lgkmcnt(0)
	v_add_f32_e32 v200, v200, v201
	v_add_f32_e32 v202, v202, v203
	v_add_f32_e32 v204, v204, v205
	v_add_f32_e32 v206, v206, v207
	v_fmamk_f32 v200, v200, 0x3a000000, v216
	v_cmp_gt_f32_e32 vcc, s65, v200
	v_mul_f32_e32 v201, 0x4b800000, v200
	s_nop 0
	v_cndmask_b32_e32 v200, v200, v201, vcc
	v_rsq_f32_e32 v200, v200
	s_nop 0
	v_mul_f32_e32 v201, 0x45800000, v200
	v_cndmask_b32_e32 v200, v200, v201, vcc
	v_fmamk_f32 v202, v202, 0x3a000000, v216
	v_cmp_gt_f32_e32 vcc, s65, v202
	v_mul_f32_e32 v203, 0x4b800000, v202
	s_nop 0
	v_cndmask_b32_e32 v202, v202, v203, vcc
	v_rsq_f32_e32 v202, v202
	s_nop 0
	v_mul_f32_e32 v203, 0x45800000, v202
	v_cndmask_b32_e32 v202, v202, v203, vcc
	v_fmamk_f32 v204, v204, 0x3a000000, v216
	v_cmp_gt_f32_e32 vcc, s65, v204
	v_mul_f32_e32 v205, 0x4b800000, v204
	s_nop 0
	v_cndmask_b32_e32 v204, v204, v205, vcc
	v_rsq_f32_e32 v204, v204
	s_nop 0
	v_mul_f32_e32 v205, 0x45800000, v204
	v_cndmask_b32_e32 v204, v204, v205, vcc
	v_fmamk_f32 v206, v206, 0x3a000000, v216
	v_cmp_gt_f32_e32 vcc, s65, v206
	v_mul_f32_e32 v207, 0x4b800000, v206
	s_nop 0
	v_cndmask_b32_e32 v206, v206, v207, vcc
	v_rsq_f32_e32 v206, v206
	s_nop 0
	v_mul_f32_e32 v207, 0x45800000, v206
	v_cndmask_b32_e32 v206, v206, v207, vcc
	v_pk_mul_f32 v[62:63], v[62:63], v[200:201] op_sel_hi:[1,0]
	v_pk_mul_f32 v[64:65], v[64:65], v[200:201] op_sel_hi:[1,0]
	v_pk_mul_f32 v[58:59], v[58:59], v[200:201] op_sel_hi:[1,0]
	v_pk_mul_f32 v[60:61], v[60:61], v[200:201] op_sel_hi:[1,0]
	v_pk_mul_f32 v[54:55], v[54:55], v[200:201] op_sel_hi:[1,0]
	v_pk_mul_f32 v[56:57], v[56:57], v[200:201] op_sel_hi:[1,0]
	v_pk_mul_f32 v[50:51], v[50:51], v[200:201] op_sel_hi:[1,0]
	v_pk_mul_f32 v[52:53], v[52:53], v[200:201] op_sel_hi:[1,0]
	v_mul_f32_e32 v208, 0xbfb8aa3b, v62
	v_mul_f32_e32 v209, 0xbfb8aa3b, v63
	v_mul_f32_e32 v210, 0xbfb8aa3b, v64
	v_mul_f32_e32 v211, 0xbfb8aa3b, v65
	v_mul_f32_e32 v232, 0xbfb8aa3b, v58
	v_mul_f32_e32 v233, 0xbfb8aa3b, v59
	v_mul_f32_e32 v234, 0xbfb8aa3b, v60
	v_mul_f32_e32 v235, 0xbfb8aa3b, v61
	v_exp_f32_e32 v208, v208
	v_exp_f32_e32 v209, v209
	v_exp_f32_e32 v210, v210
	v_exp_f32_e32 v211, v211
	v_exp_f32_e32 v232, v232
	v_exp_f32_e32 v233, v233
	v_exp_f32_e32 v234, v234
	v_exp_f32_e32 v235, v235
	v_add_f32_e32 v208, 1.0, v208
	v_add_f32_e32 v209, 1.0, v209
	v_add_f32_e32 v210, 1.0, v210
	v_add_f32_e32 v211, 1.0, v211
	v_add_f32_e32 v232, 1.0, v232
	v_add_f32_e32 v233, 1.0, v233
	v_add_f32_e32 v234, 1.0, v234
	v_add_f32_e32 v235, 1.0, v235
	v_rcp_f32_e32 v208, v208
	v_rcp_f32_e32 v209, v209
	v_rcp_f32_e32 v210, v210
	v_rcp_f32_e32 v211, v211
	v_rcp_f32_e32 v232, v232
	v_rcp_f32_e32 v233, v233
	v_rcp_f32_e32 v234, v234
	v_rcp_f32_e32 v235, v235
	v_pk_mul_f32 v[208:209], v[62:63], v[208:209]
	v_pk_mul_f32 v[210:211], v[64:65], v[210:211]
	v_pk_mul_f32 v[232:233], v[58:59], v[232:233]
	v_pk_mul_f32 v[234:235], v[60:61], v[234:235]
	v_pk_mul_f32 v[208:209], v[54:55], v[208:209]
	v_pk_mul_f32 v[210:211], v[56:57], v[210:211]
	v_pk_mul_f32 v[232:233], v[50:51], v[232:233]
	v_pk_mul_f32 v[234:235], v[52:53], v[234:235]
	v_cvt_pk_bf16_f32 v208, v208, v209
	v_cvt_pk_bf16_f32 v209, v210, v211
	v_cvt_pk_bf16_f32 v210, v232, v233
	v_cvt_pk_bf16_f32 v211, v234, v235
	v_add_u32_e32 v158, 0x80, v148
	v_mad_i64_i32 v[158:159], s[0:1], v158, s2, v[146:147]
	global_store_dwordx4 v[158:159], v[208:211], off
	v_pk_mul_f32 v[46:47], v[46:47], v[202:203] op_sel_hi:[1,0]
	v_pk_mul_f32 v[48:49], v[48:49], v[202:203] op_sel_hi:[1,0]
	v_pk_mul_f32 v[42:43], v[42:43], v[202:203] op_sel_hi:[1,0]
	v_pk_mul_f32 v[44:45], v[44:45], v[202:203] op_sel_hi:[1,0]
	v_pk_mul_f32 v[38:39], v[38:39], v[202:203] op_sel_hi:[1,0]
	v_pk_mul_f32 v[40:41], v[40:41], v[202:203] op_sel_hi:[1,0]
	v_pk_mul_f32 v[34:35], v[34:35], v[202:203] op_sel_hi:[1,0]
	v_pk_mul_f32 v[36:37], v[36:37], v[202:203] op_sel_hi:[1,0]
	v_mul_f32_e32 v208, 0xbfb8aa3b, v46
	v_mul_f32_e32 v209, 0xbfb8aa3b, v47
	v_mul_f32_e32 v210, 0xbfb8aa3b, v48
	v_mul_f32_e32 v211, 0xbfb8aa3b, v49
	v_mul_f32_e32 v232, 0xbfb8aa3b, v42
	v_mul_f32_e32 v233, 0xbfb8aa3b, v43
	v_mul_f32_e32 v234, 0xbfb8aa3b, v44
	v_mul_f32_e32 v235, 0xbfb8aa3b, v45
	v_exp_f32_e32 v208, v208
	v_exp_f32_e32 v209, v209
	v_exp_f32_e32 v210, v210
	v_exp_f32_e32 v211, v211
	v_exp_f32_e32 v232, v232
	v_exp_f32_e32 v233, v233
	v_exp_f32_e32 v234, v234
	v_exp_f32_e32 v235, v235
	v_add_f32_e32 v208, 1.0, v208
	v_add_f32_e32 v209, 1.0, v209
	v_add_f32_e32 v210, 1.0, v210
	v_add_f32_e32 v211, 1.0, v211
	v_add_f32_e32 v232, 1.0, v232
	v_add_f32_e32 v233, 1.0, v233
	v_add_f32_e32 v234, 1.0, v234
	v_add_f32_e32 v235, 1.0, v235
	v_rcp_f32_e32 v208, v208
	v_rcp_f32_e32 v209, v209
	v_rcp_f32_e32 v210, v210
	v_rcp_f32_e32 v211, v211
	v_rcp_f32_e32 v232, v232
	v_rcp_f32_e32 v233, v233
	v_rcp_f32_e32 v234, v234
	v_rcp_f32_e32 v235, v235
	v_pk_mul_f32 v[208:209], v[46:47], v[208:209]
	v_pk_mul_f32 v[210:211], v[48:49], v[210:211]
	v_pk_mul_f32 v[232:233], v[42:43], v[232:233]
	v_pk_mul_f32 v[234:235], v[44:45], v[234:235]
	v_pk_mul_f32 v[208:209], v[38:39], v[208:209]
	v_pk_mul_f32 v[210:211], v[40:41], v[210:211]
	v_pk_mul_f32 v[232:233], v[34:35], v[232:233]
	v_pk_mul_f32 v[234:235], v[36:37], v[234:235]
	v_cvt_pk_bf16_f32 v208, v208, v209
	v_cvt_pk_bf16_f32 v209, v210, v211
	v_cvt_pk_bf16_f32 v210, v232, v233
	v_cvt_pk_bf16_f32 v211, v234, v235
	v_add_u32_e32 v158, 0x90, v148
	v_mad_i64_i32 v[158:159], s[0:1], v158, s2, v[146:147]
	global_store_dwordx4 v[158:159], v[208:211], off
	v_pk_mul_f32 v[30:31], v[30:31], v[204:205] op_sel_hi:[1,0]
	v_pk_mul_f32 v[32:33], v[32:33], v[204:205] op_sel_hi:[1,0]
	v_pk_mul_f32 v[26:27], v[26:27], v[204:205] op_sel_hi:[1,0]
	v_pk_mul_f32 v[28:29], v[28:29], v[204:205] op_sel_hi:[1,0]
	v_pk_mul_f32 v[22:23], v[22:23], v[204:205] op_sel_hi:[1,0]
	v_pk_mul_f32 v[24:25], v[24:25], v[204:205] op_sel_hi:[1,0]
	v_pk_mul_f32 v[18:19], v[18:19], v[204:205] op_sel_hi:[1,0]
	v_pk_mul_f32 v[20:21], v[20:21], v[204:205] op_sel_hi:[1,0]
	v_mul_f32_e32 v208, 0xbfb8aa3b, v30
	v_mul_f32_e32 v209, 0xbfb8aa3b, v31
	v_mul_f32_e32 v210, 0xbfb8aa3b, v32
	v_mul_f32_e32 v211, 0xbfb8aa3b, v33
	v_mul_f32_e32 v232, 0xbfb8aa3b, v26
	v_mul_f32_e32 v233, 0xbfb8aa3b, v27
	v_mul_f32_e32 v234, 0xbfb8aa3b, v28
	v_mul_f32_e32 v235, 0xbfb8aa3b, v29
	v_exp_f32_e32 v208, v208
	v_exp_f32_e32 v209, v209
	v_exp_f32_e32 v210, v210
	v_exp_f32_e32 v211, v211
	v_exp_f32_e32 v232, v232
	v_exp_f32_e32 v233, v233
	v_exp_f32_e32 v234, v234
	v_exp_f32_e32 v235, v235
	v_add_f32_e32 v208, 1.0, v208
	v_add_f32_e32 v209, 1.0, v209
	v_add_f32_e32 v210, 1.0, v210
	v_add_f32_e32 v211, 1.0, v211
	v_add_f32_e32 v232, 1.0, v232
	v_add_f32_e32 v233, 1.0, v233
	v_add_f32_e32 v234, 1.0, v234
	v_add_f32_e32 v235, 1.0, v235
	v_rcp_f32_e32 v208, v208
	v_rcp_f32_e32 v209, v209
	v_rcp_f32_e32 v210, v210
	v_rcp_f32_e32 v211, v211
	v_rcp_f32_e32 v232, v232
	v_rcp_f32_e32 v233, v233
	v_rcp_f32_e32 v234, v234
	v_rcp_f32_e32 v235, v235
	v_pk_mul_f32 v[208:209], v[30:31], v[208:209]
	v_pk_mul_f32 v[210:211], v[32:33], v[210:211]
	v_pk_mul_f32 v[232:233], v[26:27], v[232:233]
	v_pk_mul_f32 v[234:235], v[28:29], v[234:235]
	v_pk_mul_f32 v[208:209], v[22:23], v[208:209]
	v_pk_mul_f32 v[210:211], v[24:25], v[210:211]
	v_pk_mul_f32 v[232:233], v[18:19], v[232:233]
	v_pk_mul_f32 v[234:235], v[20:21], v[234:235]
	v_cvt_pk_bf16_f32 v208, v208, v209
	v_cvt_pk_bf16_f32 v209, v210, v211
	v_cvt_pk_bf16_f32 v210, v232, v233
	v_cvt_pk_bf16_f32 v211, v234, v235
	v_add_u32_e32 v158, 0xa0, v148
	v_mad_i64_i32 v[158:159], s[0:1], v158, s2, v[146:147]
	global_store_dwordx4 v[158:159], v[208:211], off
	v_pk_mul_f32 v[14:15], v[14:15], v[206:207] op_sel_hi:[1,0]
	v_pk_mul_f32 v[16:17], v[16:17], v[206:207] op_sel_hi:[1,0]
	v_pk_mul_f32 v[10:11], v[10:11], v[206:207] op_sel_hi:[1,0]
	v_pk_mul_f32 v[12:13], v[12:13], v[206:207] op_sel_hi:[1,0]
	v_pk_mul_f32 v[6:7], v[6:7], v[206:207] op_sel_hi:[1,0]
	v_pk_mul_f32 v[8:9], v[8:9], v[206:207] op_sel_hi:[1,0]
	v_pk_mul_f32 v[2:3], v[2:3], v[206:207] op_sel_hi:[1,0]
	v_pk_mul_f32 v[4:5], v[4:5], v[206:207] op_sel_hi:[1,0]
	v_mul_f32_e32 v208, 0xbfb8aa3b, v14
	v_mul_f32_e32 v209, 0xbfb8aa3b, v15
	v_mul_f32_e32 v210, 0xbfb8aa3b, v16
	v_mul_f32_e32 v211, 0xbfb8aa3b, v17
	v_mul_f32_e32 v232, 0xbfb8aa3b, v10
	v_mul_f32_e32 v233, 0xbfb8aa3b, v11
	v_mul_f32_e32 v234, 0xbfb8aa3b, v12
	v_mul_f32_e32 v235, 0xbfb8aa3b, v13
	v_exp_f32_e32 v208, v208
	v_exp_f32_e32 v209, v209
	v_exp_f32_e32 v210, v210
	v_exp_f32_e32 v211, v211
	v_exp_f32_e32 v232, v232
	v_exp_f32_e32 v233, v233
	v_exp_f32_e32 v234, v234
	v_exp_f32_e32 v235, v235
	v_add_f32_e32 v208, 1.0, v208
	v_add_f32_e32 v209, 1.0, v209
	v_add_f32_e32 v210, 1.0, v210
	v_add_f32_e32 v211, 1.0, v211
	v_add_f32_e32 v232, 1.0, v232
	v_add_f32_e32 v233, 1.0, v233
	v_add_f32_e32 v234, 1.0, v234
	v_add_f32_e32 v235, 1.0, v235
	v_rcp_f32_e32 v208, v208
	v_rcp_f32_e32 v209, v209
	v_rcp_f32_e32 v210, v210
	v_rcp_f32_e32 v211, v211
	v_rcp_f32_e32 v232, v232
	v_rcp_f32_e32 v233, v233
	v_rcp_f32_e32 v234, v234
	v_rcp_f32_e32 v235, v235
	v_pk_mul_f32 v[208:209], v[14:15], v[208:209]
	v_pk_mul_f32 v[210:211], v[16:17], v[210:211]
	v_pk_mul_f32 v[232:233], v[10:11], v[232:233]
	v_pk_mul_f32 v[234:235], v[12:13], v[234:235]
	v_pk_mul_f32 v[208:209], v[6:7], v[208:209]
	v_pk_mul_f32 v[210:211], v[8:9], v[210:211]
	v_pk_mul_f32 v[232:233], v[2:3], v[232:233]
	v_pk_mul_f32 v[234:235], v[4:5], v[234:235]
	v_cvt_pk_bf16_f32 v208, v208, v209
	v_cvt_pk_bf16_f32 v209, v210, v211
	v_cvt_pk_bf16_f32 v210, v232, v233
	v_cvt_pk_bf16_f32 v211, v234, v235
	v_add_u32_e32 v158, 0xb0, v148
	v_mad_i64_i32 v[158:159], s[0:1], v158, s2, v[146:147]
	global_store_dwordx4 v[158:159], v[208:211], off
	s_mov_b64 s[0:1], -1
	s_andn2_b64 vcc, exec, s[4:5]
	s_cbranch_vccnz .LBB0_332
	s_andn2_b64 vcc, exec, s[6:7]
	s_cbranch_vccnz .LBB0_331
	s_barrier
	s_branch .LBB0_331
